# attention-phase weight-conversion filler now strided over all 256 workgroups (state-walk workgroups join after their shorter walk)
# baseline (speedup 1.0000x reference)
; __device__ __forceinline__ int otid() { int t = threadIdx.x; asm volatile("" : "+v"(t)); return t; }
; __device__ __forceinline__ int obid() { int t = blockIdx.x; asm volatile("" : "+s"(t)); return t; }
;     const int tid = otid(), lane = tid & 63, wave = tid >> 6;
;     float* scr = lds + wave * 4096;
;     const int bxw = obid();
;     const int bend = ((int)gridDim.x < nblk) ? (int)gridDim.x : nblk;
;     if (bxw < blk0 || bxw >= bend) return;
;     const int gw = (bxw - blk0) * NWAVES + wave, NGW = (bend - blk0) * NWAVES;
;     unsigned char* ws = a.ws;
;     constexpr int I_IN = 32 * 401, I_GLU = 16 * 64, I_WB = 3 * 16 * 64, I_OUT = 32 * 64, I_G = 32 * 176, I_DN = 88 * 64;
;     constexpr int TOTAL = I_IN + I_GLU + I_WB + I_OUT + 2 * I_G + I_DN;
;     for (int it = gw; it < TOTAL; it += NGW) {
; __global__ void __launch_bounds__(NT, 2) mega(Args a) {
;     ...
;         if (!last) { const int nfill = (G >= 128) ? G - 64 : G; __syncthreads(); wconv_phase(a, 0, fl, 2 | 4 | 8 | 16, 0, nfill); __syncthreads(); mod_phase(a, fl, modv, 128, 256, nfill); }
.LBB0_421:
	v_readlane_b32 s4, v255, 50
	v_readlane_b32 s5, v255, 51
	s_andn2_b64 vcc, exec, s[4:5]
	s_nop 0
	v_cndmask_b32_e64 v0, 0, 1, s[4:5]
	v_cmp_ne_u32_e64 s[0:1], 1, v0
	s_nop 1
	v_writelane_b32 v255, s0, 52
	s_nop 1
	v_writelane_b32 v255, s1, 53
	s_cbranch_vccnz .LBB0_473
	v_mov_b32_e32 v0, v188
	s_mov_b32 s0, s34
	s_barrier
	s_cmp_lt_i32 s0, 0
	v_readlane_b32 s1, v254, 4
	s_add_i32 s1, s1, 64
	s_cselect_b64 s[4:5], -1, 0
	s_cmp_ge_i32 s0, s1
	s_cselect_b64 s[6:7], -1, 0
	s_or_b64 s[4:5], s[4:5], s[6:7]
	s_and_b64 vcc, exec, s[4:5]
	s_cbranch_vccnz .LBB0_455
	v_ashrrev_i32_e32 v2, 6, v0
	v_lshl_add_u32 v33, s0, 3, v2
	s_mov_b32 s0, 0x8c20
	v_cmp_gt_i32_e32 vcc, s0, v33
	s_and_saveexec_b64 s[0:1], vcc
	v_readlane_b32 s20, v254, 49
	s_addk_i32 s20, 0x200
	s_cbranch_execz .LBB0_454
	v_bfe_u32 v30, v0, 5, 1
	v_and_b32_e32 v20, 31, v0
	v_bfe_u32 v32, v0, 3, 3
	v_lshlrev_b32_e32 v0, 3, v0
	v_and_b32_e32 v0, 56, v0
	v_readlane_b32 s4, v253, 60
	v_lshl_add_u32 v4, v2, 14, 0
	v_mul_u32_u24_e32 v2, 0x84, v30
	v_lshlrev_b32_e32 v18, 2, v20
	v_lshlrev_b32_e32 v8, 1, v0
	v_mov_b32_e32 v9, v1
	v_readlane_b32 s5, v253, 61
	v_add3_u32 v31, v4, v2, v18
	v_mul_u32_u24_e32 v5, 0x84, v0
	v_lshl_add_u64 v[2:3], s[4:5], 0, v[8:9]
	v_readlane_b32 s4, v253, 62
	v_lshlrev_b32_e32 v6, 2, v32
	v_readlane_b32 s5, v253, 63
	v_add3_u32 v34, v4, v5, v6
	v_mov_b32_e32 v19, v1
	v_lshl_add_u64 v[4:5], s[4:5], 0, v[8:9]
	v_readlane_b32 s4, v254, 0
	v_readlane_b32 s5, v254, 1
	v_or_b32_e32 v35, 8, v32
	v_or_b32_e32 v36, 16, v32
	v_lshl_add_u64 v[6:7], s[4:5], 0, v[8:9]
	v_readlane_b32 s4, v254, 2
	v_readlane_b32 s5, v254, 3
	v_or_b32_e32 v37, 24, v32
	v_lshl_add_u64 v[10:11], s[82:83], 0, v[18:19]
	v_lshl_add_u64 v[8:9], s[4:5], 0, v[8:9]
	v_readlane_b32 s4, v252, 38
	v_readlane_b32 s12, v252, 46
	v_readlane_b32 s13, v252, 47
	v_readlane_b32 s5, v252, 39
	v_readlane_b32 s10, v252, 44
	v_readlane_b32 s11, v252, 45
	v_readlane_b32 s16, v252, 50
	v_readlane_b32 s17, v252, 51
	v_readlane_b32 s18, v252, 52
	v_readlane_b32 s19, v252, 53
	v_readlane_b32 s12, v255, 32
	v_lshl_add_u64 v[12:13], s[80:81], 0, v[18:19]
	v_readlane_b32 s13, v255, 33
	v_lshl_add_u64 v[14:15], s[18:19], 0, v[18:19]
	v_lshl_add_u64 v[16:17], s[16:17], 0, v[18:19]
	v_lshl_add_u64 v[18:19], s[10:11], 0, v[18:19]
	s_mov_b64 s[4:5], 0
	v_lshlrev_b32_e32 v20, 2, v20
	v_lshlrev_b32_e32 v22, 1, v0
	v_readlane_b32 s6, v252, 40
	v_readlane_b32 s7, v252, 41
	v_readlane_b32 s8, v252, 42
	v_readlane_b32 s9, v252, 43
	v_readlane_b32 s14, v252, 48
	v_readlane_b32 s15, v252, 49
	s_branch .LBB0_426

;     ...
;         if (r < I_IN) { if (!(parts & (1 | 32 | 64))) { it += (I_IN - r - 1) / NGW * NGW; continue; }
.LBB0_452:
	s_andn2_saveexec_b64 s[6:7], s[6:7]
	s_cbranch_execz .LBB0_425
	v_sub_u32_e32 v0, 0x321f, v33
	v_and_b32_e32 v0, 0x7ff, v0
	v_sub_u32_e32 v33, 0x321f, v0
	s_branch .LBB0_425
